# fix: tail-done counters moved off the seam-10 group-barrier counter words (seam 10 is now a real group barrier for every group)
# baseline (speedup 1.0000x reference)
.Lmy_td2:
	s_waitcnt vmcnt(0)
	s_mov_b64 s[6:7], exec
	s_mov_b64 exec, 1
	v_mov_b32_e32 v2, 0x37000
	v_mov_b32_e32 v3, 1
	global_atomic_add v2, v3, s[50:51]
	s_mov_b64 exec, s[6:7]

.Lmy_gb2_go:
	v_mov_b32_e32 v2, 0x37000
	s_movk_i32 s7, 0x4000

.Lmy_td10:
	s_waitcnt vmcnt(0)
	s_mov_b64 s[6:7], exec
	s_mov_b64 exec, 1
	v_mov_b32_e32 v2, 0x37100
	v_mov_b32_e32 v3, 1
	global_atomic_add v2, v3, s[50:51]
	s_mov_b64 exec, s[6:7]

.Lmy_gb10_go:
	v_mov_b32_e32 v2, 0x37100
	s_movk_i32 s7, 0x4000
